# diff-attn: first four Q fragments kept resident in spare VGPRs instead of re-read from LDS every key tile
# speedup vs baseline: 1.0427x; 1.0038x over previous
; template <int KS, int NMAP, int EB, int NKB, int MODE>
; DI void attn_unit(unsigned char* smem, const AttnArgs& a, int t0, int head, int ehalf) {
;     ...
;   if (QLDS) {
; #pragma unroll
;     for (int s = 0; s < NMAP * KS; ++s) *(bf16x8*)(qs + qoff + s * 32) = *(const bf16x8*)(qrow + 16 * s + 8 * h);
;     ...
;   for (int eh = 0; eh < (MODE == AT_XA ? 2 : 1); ++eh) {
;   if (MODE == AT_XA && eh == 1) { vbase += 4096; orow += 128; }
;   f32x16 oacc[NMAP][EB];
; #pragma unroll
;   for (int c = 0; c < NMAP; ++c)
; #pragma unroll
;     for (int e = 0; e < EB; ++e)
; #pragma unroll
;       for (int i = 0; i < 16; ++i) oacc[c][e][i] = 0.f;
;   float lsum[NMAP];
; #pragma unroll
;   for (int c = 0; c < NMAP; ++c) lsum[c] = 0.f;
;   const float negM = -a.M;
;   u32x4 rk[NK_PER], rv[NV_PER];
;     ...
;   constexpr bool DBUF = (MODE != AT_XA);
;   AT_LOAD(kt_lo * KT);
;   if (DBUF) {
;     AT_WRITE(0);
;     if (kt_lo + 1 < kt_hi) AT_LOAD((kt_lo + 1) * KT);
;     __syncthreads();
;   }
;   for (int kt = kt_lo; kt < kt_hi; ++kt) {
;     const int cur = DBUF ? ((kt - kt_lo) & 1) : 0;
;     const unsigned char* ks = smem + cur * TILEB; const unsigned char* vs = ks + KT * KP;
.LBB0_406:
	v_mov_b32_e32 v177, 0
	v_lshlrev_b32_e32 v174, 3, v0
	s_cmp_ge_i32 s50, s13
	v_mov_b32_e32 v176, v177
	v_mov_b32_e32 v31, v177
	v_mov_b32_e32 v30, v177
	v_mov_b32_e32 v29, v177
	v_mov_b32_e32 v28, v177
	v_mov_b32_e32 v27, v177
	v_mov_b32_e32 v26, v177
	v_mov_b32_e32 v25, v177
	v_mov_b32_e32 v24, v177
	v_mov_b32_e32 v23, v177
	v_mov_b32_e32 v22, v177
	v_mov_b32_e32 v21, v177
	v_mov_b32_e32 v20, v177
	v_mov_b32_e32 v19, v177
	v_mov_b32_e32 v18, v177
	v_mov_b32_e32 v17, v177
	v_mov_b32_e32 v16, v177
	v_mov_b32_e32 v63, v177
	v_mov_b32_e32 v62, v177
	v_mov_b32_e32 v61, v177
	v_mov_b32_e32 v60, v177
	v_mov_b32_e32 v59, v177
	v_mov_b32_e32 v58, v177
	v_mov_b32_e32 v57, v177
	v_mov_b32_e32 v56, v177
	v_mov_b32_e32 v55, v177
	v_mov_b32_e32 v54, v177
	v_mov_b32_e32 v53, v177
	v_mov_b32_e32 v52, v177
	v_mov_b32_e32 v51, v177
	v_mov_b32_e32 v50, v177
	v_mov_b32_e32 v49, v177
	v_mov_b32_e32 v48, v177
	v_mov_b32_e32 v95, v177
	v_mov_b32_e32 v94, v177
	v_mov_b32_e32 v93, v177
	v_mov_b32_e32 v92, v177
	v_mov_b32_e32 v91, v177
	v_mov_b32_e32 v90, v177
	v_mov_b32_e32 v89, v177
	v_mov_b32_e32 v88, v177
	v_mov_b32_e32 v87, v177
	v_mov_b32_e32 v86, v177
	v_mov_b32_e32 v85, v177
	v_mov_b32_e32 v84, v177
	v_mov_b32_e32 v83, v177
	v_mov_b32_e32 v82, v177
	v_mov_b32_e32 v81, v177
	v_mov_b32_e32 v80, v177
	v_mov_b32_e32 v127, v177
	v_mov_b32_e32 v126, v177
	v_mov_b32_e32 v125, v177
	v_mov_b32_e32 v124, v177
	v_mov_b32_e32 v123, v177
	v_mov_b32_e32 v122, v177
	v_mov_b32_e32 v121, v177
	v_mov_b32_e32 v120, v177
	v_mov_b32_e32 v119, v177
	v_mov_b32_e32 v118, v177
	v_mov_b32_e32 v117, v177
	v_mov_b32_e32 v116, v177
	v_mov_b32_e32 v115, v177
	v_mov_b32_e32 v114, v177
	v_mov_b32_e32 v113, v177
	v_mov_b32_e32 v112, v177
	v_mov_b32_e32 v15, v177
	v_mov_b32_e32 v14, v177
	v_mov_b32_e32 v13, v177
	v_mov_b32_e32 v12, v177
	v_mov_b32_e32 v11, v177
	v_mov_b32_e32 v10, v177
	v_mov_b32_e32 v9, v177
	v_mov_b32_e32 v8, v177
	v_mov_b32_e32 v7, v177
	v_mov_b32_e32 v6, v177
	v_mov_b32_e32 v5, v177
	v_mov_b32_e32 v4, v177
	v_mov_b32_e32 v3, v177
	v_mov_b32_e32 v2, v177
	v_mov_b32_e32 v1, v177
	v_mov_b32_e32 v0, v177
	v_mov_b32_e32 v47, v177
	v_mov_b32_e32 v46, v177
	v_mov_b32_e32 v45, v177
	v_mov_b32_e32 v44, v177
	v_mov_b32_e32 v43, v177
	v_mov_b32_e32 v42, v177
	v_mov_b32_e32 v41, v177
	v_mov_b32_e32 v40, v177
	v_mov_b32_e32 v39, v177
	v_mov_b32_e32 v38, v177
	v_mov_b32_e32 v37, v177
	v_mov_b32_e32 v36, v177
	v_mov_b32_e32 v35, v177
	v_mov_b32_e32 v34, v177
	v_mov_b32_e32 v33, v177
	v_mov_b32_e32 v32, v177
	v_mov_b32_e32 v111, v177
	v_mov_b32_e32 v110, v177
	v_mov_b32_e32 v109, v177
	v_mov_b32_e32 v108, v177
	v_mov_b32_e32 v107, v177
	v_mov_b32_e32 v106, v177
	v_mov_b32_e32 v105, v177
	v_mov_b32_e32 v104, v177
	v_mov_b32_e32 v103, v177
	v_mov_b32_e32 v102, v177
	v_mov_b32_e32 v101, v177
	v_mov_b32_e32 v100, v177
	v_mov_b32_e32 v99, v177
	v_mov_b32_e32 v98, v177
	v_mov_b32_e32 v97, v177
	v_mov_b32_e32 v96, v177
	v_mov_b32_e32 v79, v177
	v_mov_b32_e32 v78, v177
	v_mov_b32_e32 v77, v177
	v_mov_b32_e32 v76, v177
	v_mov_b32_e32 v75, v177
	v_mov_b32_e32 v74, v177
	v_mov_b32_e32 v73, v177
	v_mov_b32_e32 v72, v177
	v_mov_b32_e32 v71, v177
	v_mov_b32_e32 v70, v177
	v_mov_b32_e32 v69, v177
	v_mov_b32_e32 v68, v177
	v_mov_b32_e32 v67, v177
	v_mov_b32_e32 v66, v177
	v_mov_b32_e32 v65, v177
	v_mov_b32_e32 v64, v177
	s_waitcnt lgkmcnt(0)
	s_barrier
	s_cbranch_scc1 .LBB0_396
	ds_read_b128 v[228:231], v175 offset:37888
	ds_read_b128 v[232:235], v175 offset:37920
	ds_read_b128 v[236:239], v175 offset:37952
	ds_read_b128 v[240:243], v175 offset:37984
	v_and_b32_e32 v0, 31, v132
	v_and_b32_e32 v1, 0xffffffe0, v133
	v_mul_u32_u24_e32 v195, 0x110, v0
	v_mul_u32_u24_e32 v196, 0x50, v0
	v_add3_u32 v0, s33, v1, v0
	v_subrev_u32_e32 v0, s12, v0
	s_lshl_b32 s12, s50, 5
	s_lshl_b64 s[0:1], s[50:51], 13
	s_add_u32 s0, s0, s14
	s_addc_u32 s1, s1, s15
	s_add_u32 s0, s0, s16
	s_addc_u32 s1, s1, s17
	s_add_u32 s0, s48, s0
	v_xor_b32_e32 v180, 0x80000000, v134
	v_sub_u32_e32 v0, v0, v174
	s_addc_u32 s1, s49, s1
	v_mov_b32_e32 v64, 0
	v_lshl_add_u64 v[178:179], v[130:131], 1, s[20:21]
	v_mov_b32_e32 v182, v180
	v_mov_b32_e32 v183, v180
	v_add_u32_e32 v197, 0, v216
	v_subrev_u32_e32 v198, s12, v0
	v_lshl_add_u64 v[184:185], v[128:129], 1, s[0:1]
	v_add3_u32 v186, v135, s12, 64
	s_mov_b32 s12, 0
	v_mov_b32_e32 v65, v64
	v_mov_b32_e32 v66, v64
	v_mov_b32_e32 v67, v64
	v_mov_b32_e32 v68, v64
	v_mov_b32_e32 v69, v64
	v_mov_b32_e32 v70, v64
	v_mov_b32_e32 v71, v64
	v_mov_b32_e32 v72, v64
	v_mov_b32_e32 v73, v64
	v_mov_b32_e32 v74, v64
	v_mov_b32_e32 v75, v64
	v_mov_b32_e32 v76, v64
	v_mov_b32_e32 v77, v64
	v_mov_b32_e32 v78, v64
	v_mov_b32_e32 v79, v64
	v_mov_b32_e32 v96, v64
	v_mov_b32_e32 v97, v64
	v_mov_b32_e32 v98, v64
	v_mov_b32_e32 v99, v64
	v_mov_b32_e32 v100, v64
	v_mov_b32_e32 v101, v64
	v_mov_b32_e32 v102, v64
	v_mov_b32_e32 v103, v64
	v_mov_b32_e32 v104, v64
	v_mov_b32_e32 v105, v64
	v_mov_b32_e32 v106, v64
	v_mov_b32_e32 v107, v64
	v_mov_b32_e32 v108, v64
	v_mov_b32_e32 v109, v64
	v_mov_b32_e32 v110, v64
	v_mov_b32_e32 v111, v64
	v_mov_b32_e32 v32, v64
	v_mov_b32_e32 v33, v64
	v_mov_b32_e32 v34, v64
	v_mov_b32_e32 v35, v64
	v_mov_b32_e32 v36, v64
	v_mov_b32_e32 v37, v64
	v_mov_b32_e32 v38, v64
	v_mov_b32_e32 v39, v64
	v_mov_b32_e32 v40, v64
	v_mov_b32_e32 v41, v64
	v_mov_b32_e32 v42, v64
	v_mov_b32_e32 v43, v64
	v_mov_b32_e32 v44, v64
	v_mov_b32_e32 v45, v64
	v_mov_b32_e32 v46, v64
	v_mov_b32_e32 v47, v64
	v_mov_b32_e32 v0, v64
	v_mov_b32_e32 v1, v64
	v_mov_b32_e32 v2, v64
	v_mov_b32_e32 v3, v64
	v_mov_b32_e32 v4, v64
	v_mov_b32_e32 v5, v64
	v_mov_b32_e32 v6, v64
	v_mov_b32_e32 v7, v64
; template <int KS, int NMAP, int EB, int NKB, int MODE>
; DI void attn_unit(unsigned char* smem, const AttnArgs& a, int t0, int head, int ehalf) {
;     ...
;   f32x16 oacc[NMAP][EB];
; #pragma unroll
;   for (int c = 0; c < NMAP; ++c)
; #pragma unroll
;     for (int e = 0; e < EB; ++e)
; #pragma unroll
;       for (int i = 0; i < 16; ++i) oacc[c][e][i] = 0.f;
;   float lsum[NMAP];
; #pragma unroll
;   for (int c = 0; c < NMAP; ++c) lsum[c] = 0.f;
	v_mov_b32_e32 v8, v64
	v_mov_b32_e32 v9, v64
	v_mov_b32_e32 v10, v64
	v_mov_b32_e32 v11, v64
	v_mov_b32_e32 v12, v64
	v_mov_b32_e32 v13, v64
	v_mov_b32_e32 v14, v64
	v_mov_b32_e32 v15, v64
	v_mov_b32_e32 v112, v64
	v_mov_b32_e32 v113, v64
	v_mov_b32_e32 v114, v64
	v_mov_b32_e32 v115, v64
	v_mov_b32_e32 v116, v64
	v_mov_b32_e32 v117, v64
	v_mov_b32_e32 v118, v64
	v_mov_b32_e32 v119, v64
	v_mov_b32_e32 v120, v64
	v_mov_b32_e32 v121, v64
	v_mov_b32_e32 v122, v64
	v_mov_b32_e32 v123, v64
	v_mov_b32_e32 v124, v64
	v_mov_b32_e32 v125, v64
	v_mov_b32_e32 v126, v64
	v_mov_b32_e32 v127, v64
	v_mov_b32_e32 v80, v64
	v_mov_b32_e32 v81, v64
	v_mov_b32_e32 v82, v64
	v_mov_b32_e32 v83, v64
	v_mov_b32_e32 v84, v64
	v_mov_b32_e32 v85, v64
	v_mov_b32_e32 v86, v64
	v_mov_b32_e32 v87, v64
	v_mov_b32_e32 v88, v64
	v_mov_b32_e32 v89, v64
	v_mov_b32_e32 v90, v64
	v_mov_b32_e32 v91, v64
	v_mov_b32_e32 v92, v64
	v_mov_b32_e32 v93, v64
	v_mov_b32_e32 v94, v64
	v_mov_b32_e32 v95, v64
	v_mov_b32_e32 v48, v64
	v_mov_b32_e32 v49, v64
	v_mov_b32_e32 v50, v64
	v_mov_b32_e32 v51, v64
	v_mov_b32_e32 v52, v64
	v_mov_b32_e32 v53, v64
	v_mov_b32_e32 v54, v64
	v_mov_b32_e32 v55, v64
	v_mov_b32_e32 v56, v64
	v_mov_b32_e32 v57, v64
	v_mov_b32_e32 v58, v64
	v_mov_b32_e32 v59, v64
	v_mov_b32_e32 v60, v64
	v_mov_b32_e32 v61, v64
	v_mov_b32_e32 v62, v64
	v_mov_b32_e32 v63, v64
	v_mov_b32_e32 v16, v64
	v_mov_b32_e32 v17, v64
	v_mov_b32_e32 v18, v64
	v_mov_b32_e32 v19, v64
	v_mov_b32_e32 v20, v64
	v_mov_b32_e32 v21, v64
	v_mov_b32_e32 v22, v64
	v_mov_b32_e32 v23, v64
	v_mov_b32_e32 v24, v64
	v_mov_b32_e32 v25, v64
	v_mov_b32_e32 v26, v64
	v_mov_b32_e32 v27, v64
	v_mov_b32_e32 v28, v64
	v_mov_b32_e32 v29, v64
	v_mov_b32_e32 v30, v64
	v_mov_b32_e32 v31, v64
	v_mov_b32_e32 v176, v64
	v_mov_b32_e32 v177, v64
	s_branch .LBB0_409
; #define MFMA(a, b, c) __builtin_amdgcn_mfma_f32_32x32x16_bf16((a), (b), (c), 0, 0, 0)
; template <int KS, int NMAP, int EB, int NKB, int MODE>
; DI void attn_unit(unsigned char* smem, const AttnArgs& a, int t0, int head, int ehalf) {
;     ...
;     for (int kb = 0; kb < NKB; ++kb) {
;       bf16x8 pf[NMAP][2];
;       f32x16 cinit;
;       if (MODE == AT_DIFF) {
;         const float dbase = (float)(posq - kt * KT - 32 * kb - 8 * h);
; #pragma unroll
;         for (int i = 0; i < 16; ++i) { const float d = dbase - (float)(16 * (i >> 3) + (i & 7)); cinit[i] = fmaf(-slope2, fabsf(d), negM); }
;       } else {
; #pragma unroll
;         for (int i = 0; i < 16; ++i) cinit[i] = negM;
;       }
; #pragma unroll
;       for (int c = 0; c < NMAP; ++c) {
;         f32x16 sacc;
; #pragma unroll
;         for (int s = 0; s < KS; ++s) {
;           const bf16x8 kf = *(const bf16x8*)(ks + (32 * kb + r) * KP + (c * KS + s) * 32 + 16 * h);
;           const bf16x8 qv = QLDS ? *(const bf16x8*)(qs + qoff + (c * KS + s) * 32) : qf[QLDS ? 0 : c * KS + s];
;           sacc = (s == 0) ? MFMA(kf, qv, cinit) : MFMA(kf, qv, sacc);
;         }
;         float ls = 0.f;
; #pragma unroll
;         for (int i = 0; i < 16; ++i) { sacc[i] = __builtin_amdgcn_exp2f(sacc[i]); ls += sacc[i]; }
;         lsum[c] += ls;
; #pragma unroll
;         for (int cc = 0; cc < 2; ++cc) { u32x4 u;
; #pragma unroll
;           for (int j = 0; j < 4; ++j) u[j] = pk2(sacc[8 * cc + 2 * j], sacc[8 * cc + 2 * j + 1]);
;           pf[c][cc] = __builtin_bit_cast(bf16x8, u); }
;       }
; #pragma unroll
;       for (int eb = 0; eb < EB; ++eb)
; #pragma unroll
;         for (int cc = 0; cc < 2; ++cc) {
;           const bf16x8 vf = *(const bf16x8*)(vs + (eb * 32 + r) * VP + (32 * kb + 16 * cc + 8 * h) * 2);
; #pragma unroll
;           for (int c = 0; c < NMAP; ++c) oacc[c][eb] = MFMA(vf, pf[c][cc], oacc[c][eb]);
;         }
;     }
;     if (DBUF) __syncthreads();
.LBB0_408:
	s_mulk_i32 s0, 0x4a00
	v_cvt_f32_i32_e32 v128, v198
	v_add_u32_e32 v187, s0, v197
	v_add_u32_e32 v199, v187, v195
	ds_read_b128 v[208:211], v199
	ds_read_b128 v[212:215], v199 offset:32
	v_add_f32_e32 v129, -1.0, v128
	v_pk_add_f32 v[130:131], v[128:129], s[38:39] op_sel_hi:[0,1]
	v_pk_add_f32 v[132:133], v[128:129], s[78:79] op_sel_hi:[0,1]
	v_pk_add_f32 v[134:135], v[128:129], s[80:81] op_sel_hi:[0,1]
	v_pk_add_f32 v[136:137], v[128:129], s[82:83] op_sel_hi:[0,1]
	v_pk_add_f32 v[138:139], v[128:129], s[84:85] op_sel_hi:[0,1]
	v_pk_add_f32 v[140:141], v[128:129], s[86:87] op_sel_hi:[0,1]
	v_pk_add_f32 v[142:143], v[128:129], s[88:89] op_sel_hi:[0,1]
	v_fma_f32 v143, v180, |v143|, v168
	v_fma_f32 v142, v180, |v142|, v168
	v_fma_f32 v141, v180, |v141|, v168
	v_fma_f32 v140, v180, |v140|, v168
	v_fma_f32 v139, v180, |v139|, v168
	v_fma_f32 v138, v180, |v138|, v168
	v_fma_f32 v137, v180, |v137|, v168
	v_fma_f32 v136, v180, |v136|, v168
	v_fma_f32 v135, v180, |v135|, v168
	v_fma_f32 v134, v180, |v134|, v168
	v_fma_f32 v133, v180, |v133|, v168
	v_fma_f32 v132, v180, |v132|, v168
	v_fma_f32 v131, v180, |v131|, v168
	v_fma_f32 v130, v180, |v130|, v168
	v_fma_f32 v129, v180, |v129|, v168
	v_fma_f32 v128, v180, |v128|, v168
	s_mov_b64 s[0:1], 0x2000
	s_add_i32 s12, s12, 1
	s_waitcnt lgkmcnt(1)
	v_mfma_f32_32x32x16_bf16 v[144:159], v[208:211], v[228:231], v[128:143]
	v_lshl_add_u64 v[184:185], v[184:185], 0, s[0:1]
	s_add_i32 s0, s50, s12
	v_subrev_u32_e32 v198, 32, v198
	v_add_u32_e32 v186, 32, v186
	s_cmp_ge_i32 s0, s13
	s_waitcnt lgkmcnt(0)
	v_mfma_f32_32x32x16_bf16 v[144:159], v[212:215], v[232:235], v[144:159]
	ds_read_b128 v[204:207], v199 offset:64
	s_waitcnt lgkmcnt(0)
	v_mfma_f32_32x32x16_bf16 v[144:159], v[204:207], v[236:239], v[144:159]
	ds_read_b128 v[204:207], v199 offset:96
	s_waitcnt lgkmcnt(0)
	v_mfma_f32_32x32x16_bf16 v[144:159], v[204:207], v[240:243], v[144:159]
	s_nop 11
	v_exp_f32_e32 v201, v144
	v_exp_f32_e32 v203, v145
	v_exp_f32_e32 v205, v146
	v_exp_f32_e32 v207, v147
	v_exp_f32_e32 v209, v148
	v_exp_f32_e32 v211, v149
	v_exp_f32_e32 v213, v150
	v_exp_f32_e32 v215, v151
	ds_read_b128 v[144:147], v175 offset:38016
	ds_read_b128 v[148:151], v199 offset:128
	s_waitcnt lgkmcnt(0)
	v_mfma_f32_32x32x16_bf16 v[128:143], v[148:151], v[144:147], v[128:143]
	ds_read_b128 v[144:147], v175 offset:38048
	ds_read_b128 v[148:151], v199 offset:160
	v_exp_f32_e32 v221, v152
	v_exp_f32_e32 v153, v153
	v_exp_f32_e32 v223, v154
	v_exp_f32_e32 v155, v155
	v_exp_f32_e32 v225, v156
	v_exp_f32_e32 v157, v157
	s_waitcnt lgkmcnt(0)
	v_mfma_f32_32x32x16_bf16 v[128:143], v[148:151], v[144:147], v[128:143]
	ds_read_b128 v[144:147], v175 offset:38080
	ds_read_b128 v[148:151], v199 offset:192
	v_exp_f32_e32 v227, v158
	v_exp_f32_e32 v159, v159
	s_waitcnt lgkmcnt(0)
	v_mfma_f32_32x32x16_bf16 v[128:143], v[148:151], v[144:147], v[128:143]
	ds_read_b128 v[144:147], v175 offset:38112
	ds_read_b128 v[148:151], v199 offset:224
	s_waitcnt lgkmcnt(0)
	v_mfma_f32_32x32x16_bf16 v[128:143], v[148:151], v[144:147], v[128:143]
	v_cvt_pk_bf16_f32 v144, v201, v203
	v_cvt_pk_bf16_f32 v145, v205, v207
	v_cvt_pk_bf16_f32 v146, v209, v211
	v_cvt_pk_bf16_f32 v147, v213, v215
	s_nop 7
	v_exp_f32_e32 v200, v128
	v_exp_f32_e32 v202, v129
	v_exp_f32_e32 v204, v130
	v_exp_f32_e32 v206, v131
	v_exp_f32_e32 v208, v132
	v_pk_add_f32 v[128:129], v[200:201], 0 op_sel_hi:[1,0]
	v_exp_f32_e32 v210, v133
	v_pk_add_f32 v[128:129], v[202:203], v[128:129]
	v_exp_f32_e32 v212, v134
	v_pk_add_f32 v[128:129], v[204:205], v[128:129]
	v_exp_f32_e32 v214, v135
	v_pk_add_f32 v[128:129], v[206:207], v[128:129]
	v_exp_f32_e32 v220, v136
	v_pk_add_f32 v[128:129], v[208:209], v[128:129]
	v_exp_f32_e32 v152, v137
	v_pk_add_f32 v[128:129], v[210:211], v[128:129]
	v_exp_f32_e32 v222, v138
	v_pk_add_f32 v[128:129], v[212:213], v[128:129]
	v_exp_f32_e32 v154, v139
	v_pk_add_f32 v[128:129], v[214:215], v[128:129]
	v_exp_f32_e32 v224, v140
	v_pk_add_f32 v[128:129], v[220:221], v[128:129]
	v_exp_f32_e32 v156, v141
	v_pk_add_f32 v[128:129], v[152:153], v[128:129]
	v_exp_f32_e32 v226, v142
	v_pk_add_f32 v[128:129], v[222:223], v[128:129]
	v_exp_f32_e32 v158, v143
	v_pk_add_f32 v[128:129], v[154:155], v[128:129]
	v_cvt_pk_bf16_f32 v136, v200, v202
	v_pk_add_f32 v[128:129], v[224:225], v[128:129]
	v_cvt_pk_bf16_f32 v137, v204, v206
	v_pk_add_f32 v[128:129], v[156:157], v[128:129]
	v_cvt_pk_bf16_f32 v138, v208, v210
	v_pk_add_f32 v[128:129], v[226:227], v[128:129]
	v_cvt_pk_bf16_f32 v139, v212, v214
	v_pk_add_f32 v[132:133], v[158:159], v[128:129]
	v_cvt_pk_bf16_f32 v128, v221, v153
	v_pk_add_f32 v[176:177], v[176:177], v[132:133]
	v_cvt_pk_bf16_f32 v132, v220, v152
	v_add_u32_e32 v152, v187, v196
	ds_read_b128 v[140:143], v152 offset:8704
	ds_read_b128 v[148:151], v152 offset:8736
	s_waitcnt lgkmcnt(1)
	v_mfma_f32_32x32x16_bf16 v[96:111], v[140:143], v[144:147], v[96:111]
	v_cvt_pk_bf16_f32 v129, v223, v155
	v_cvt_pk_bf16_f32 v130, v225, v157
	v_cvt_pk_bf16_f32 v131, v227, v159
	v_cvt_pk_bf16_f32 v133, v222, v154
	v_cvt_pk_bf16_f32 v134, v224, v156
	v_cvt_pk_bf16_f32 v135, v226, v158
	v_mfma_f32_32x32x16_bf16 v[112:127], v[140:143], v[136:139], v[112:127]
	ds_read_b128 v[140:143], v152 offset:11264
	s_waitcnt lgkmcnt(0)
	v_mfma_f32_32x32x16_bf16 v[64:79], v[140:143], v[144:147], v[64:79]
	v_mfma_f32_32x32x16_bf16 v[80:95], v[140:143], v[136:139], v[80:95]
	ds_read_b128 v[140:143], v152 offset:11296
	s_waitcnt lgkmcnt(0)
	v_mfma_f32_32x32x16_bf16 v[64:79], v[140:143], v[128:131], v[64:79]
	v_mfma_f32_32x32x16_bf16 v[80:95], v[140:143], v[132:135], v[80:95]
	ds_read_b128 v[140:143], v152 offset:13824
	s_waitcnt lgkmcnt(0)
	v_mfma_f32_32x32x16_bf16 v[32:47], v[140:143], v[144:147], v[32:47]
	v_mfma_f32_32x32x16_bf16 v[48:63], v[140:143], v[136:139], v[48:63]
	ds_read_b128 v[140:143], v152 offset:13856
	s_waitcnt lgkmcnt(0)
	v_mfma_f32_32x32x16_bf16 v[32:47], v[140:143], v[128:131], v[32:47]
	v_mfma_f32_32x32x16_bf16 v[48:63], v[140:143], v[132:135], v[48:63]
	ds_read_b128 v[140:143], v152 offset:16384
	s_waitcnt lgkmcnt(0)
	v_mfma_f32_32x32x16_bf16 v[16:31], v[140:143], v[136:139], v[16:31]
	ds_read_b128 v[136:139], v152 offset:16416
	s_waitcnt lgkmcnt(0)
	s_barrier
	v_mfma_f32_32x32x16_bf16 v[0:15], v[140:143], v[144:147], v[0:15]
	v_mfma_f32_32x32x16_bf16 v[96:111], v[148:151], v[128:131], v[96:111]
	v_mfma_f32_32x32x16_bf16 v[112:127], v[148:151], v[132:135], v[112:127]
	v_mfma_f32_32x32x16_bf16 v[0:15], v[136:139], v[128:131], v[0:15]
	v_mfma_f32_32x32x16_bf16 v[16:31], v[136:139], v[132:135], v[16:31]
	s_cbranch_scc1 .LBB0_396
